# v013 with the P.V MFMAs alternating between two output blocks (each accumulator re-used at distance 2, like the QK^T stream)
# baseline (speedup 1.0000x reference)
.LBB0_394:
	s_sub_i32 s10, s54, 63
	s_cmp_le_i32 s10, s5
	s_cselect_b64 s[76:77], -1, 0
	s_cmp_gt_i32 s10, s5
	s_cbranch_scc1 .Lh1_skip_g3
	v_mfma_f32_32x32x16_bf16 v[48:63], v[26:29], v[236:239], v[48:63]
	ds_read_b128 v[236:239], v196 offset:57344
	v_mfma_f32_32x32x16_bf16 v[32:47], v[26:29], v[240:243], v[32:47]
	ds_read_b128 v[240:243], v207 offset:12288
	v_mfma_f32_32x32x16_bf16 v[48:63], v[168:171], v[246:249], v[48:63]
	ds_read_b128 v[246:249], v197 offset:57344
	v_mfma_f32_32x32x16_bf16 v[32:47], v[168:171], v[250:253], v[32:47]
	ds_read_b128 v[250:253], v205 offset:12288
	ds_read_b128 v[6:9], v195
	ds_read_b128 v[10:13], v195 offset:1024
	ds_read_b128 v[2:5], v195 offset:2048
	v_cmp_gt_f32_e32 vcc, 1.0, v235
	s_cbranch_vccz .Lqh1_norsc
	s_and_saveexec_b64 s[78:79], s[8:9]
	ds_write_b32 v192, v235 offset:128
	s_or_b64 exec, exec, s[78:79]
	s_waitcnt lgkmcnt(0)
	ds_read_b128 v[18:21], v189 offset:224
	ds_read_b128 v[22:25], v189 offset:192
	ds_read_b128 v[26:29], v189 offset:160
	ds_read_b128 v[168:171], v189 offset:128
	s_waitcnt lgkmcnt(3)
	v_pk_mul_f32 v[94:95], v[94:95], v[20:21]
	s_waitcnt lgkmcnt(2)
	v_pk_mul_f32 v[90:91], v[90:91], v[24:25]
	s_waitcnt lgkmcnt(1)
	v_pk_mul_f32 v[86:87], v[86:87], v[28:29]
	s_waitcnt lgkmcnt(0)
	v_pk_mul_f32 v[82:83], v[82:83], v[170:171]
	v_pk_mul_f32 v[92:93], v[92:93], v[18:19]
	v_pk_mul_f32 v[88:89], v[88:89], v[22:23]
	v_pk_mul_f32 v[84:85], v[84:85], v[26:27]
	v_pk_mul_f32 v[80:81], v[80:81], v[168:169]
	v_pk_mul_f32 v[78:79], v[78:79], v[20:21]
	v_pk_mul_f32 v[74:75], v[74:75], v[24:25]
	v_pk_mul_f32 v[70:71], v[70:71], v[28:29]
	v_pk_mul_f32 v[66:67], v[66:67], v[170:171]
	v_pk_mul_f32 v[76:77], v[76:77], v[18:19]
	v_pk_mul_f32 v[72:73], v[72:73], v[22:23]
	v_pk_mul_f32 v[68:69], v[68:69], v[26:27]
	v_pk_mul_f32 v[64:65], v[64:65], v[168:169]
	v_pk_mul_f32 v[62:63], v[62:63], v[20:21]
	v_pk_mul_f32 v[58:59], v[58:59], v[24:25]
	v_pk_mul_f32 v[54:55], v[54:55], v[28:29]
	v_pk_mul_f32 v[50:51], v[50:51], v[170:171]
	v_pk_mul_f32 v[60:61], v[60:61], v[18:19]
	v_pk_mul_f32 v[56:57], v[56:57], v[22:23]
	v_pk_mul_f32 v[52:53], v[52:53], v[26:27]
	v_pk_mul_f32 v[48:49], v[48:49], v[168:169]
	v_pk_mul_f32 v[46:47], v[46:47], v[20:21]
	v_pk_mul_f32 v[42:43], v[42:43], v[24:25]
	v_pk_mul_f32 v[38:39], v[38:39], v[28:29]
	v_pk_mul_f32 v[34:35], v[34:35], v[170:171]
	v_pk_mul_f32 v[44:45], v[44:45], v[18:19]
	v_pk_mul_f32 v[40:41], v[40:41], v[22:23]
	v_pk_mul_f32 v[36:37], v[36:37], v[26:27]
	v_pk_mul_f32 v[32:33], v[32:33], v[168:169]

.Lh1_skip_g3:
	s_cmp_eq_u32 s98, 0
	s_cbranch_scc1 .Lsk1_ng3
	v_mfma_f32_32x32x16_bf16 v[48:63], v[26:29], v[236:239], v[48:63]
	v_mfma_f32_32x32x16_bf16 v[32:47], v[26:29], v[240:243], v[32:47]
	v_mfma_f32_32x32x16_bf16 v[48:63], v[168:171], v[246:249], v[48:63]
	v_mfma_f32_32x32x16_bf16 v[32:47], v[168:171], v[250:253], v[32:47]

.Lh1_nomask:
	s_mov_b32 s98, 0
	s_add_i32 s10, s54, 0xffffff81
	s_cmp_gt_i32 s10, s5
	s_cbranch_scc1 .Lh1_nopv
	s_mov_b32 s98, 1
	ds_read_b64_tr_b16 v[236:237], v190 offset:0
	ds_read_b64_tr_b16 v[238:239], v190 offset:2048
	ds_read_b64_tr_b16 v[240:241], v190 offset:512
	ds_read_b64_tr_b16 v[242:243], v190 offset:2560
	ds_read_b64_tr_b16 v[246:247], v190 offset:4096
	ds_read_b64_tr_b16 v[248:249], v190 offset:6144
	ds_read_b64_tr_b16 v[250:251], v190 offset:4608
	ds_read_b64_tr_b16 v[252:253], v190 offset:6656
	v_max_f32_e32 v15, v113, v113
	v_max_f32_e32 v17, v112, v112
	v_max_f32_e32 v15, v17, v15
	v_max3_f32 v15, v15, v114, v115
	v_max3_f32 v15, v15, v116, v117
	v_max3_f32 v15, v15, v118, v119
	v_max3_f32 v15, v15, v120, v121
	v_max3_f32 v15, v15, v122, v123
	v_max3_f32 v15, v15, v124, v125
	v_max3_f32 v15, v15, v126, v127
	v_max3_f32 v15, v15, v96, v97
	v_max3_f32 v15, v15, v98, v99
	v_max3_f32 v15, v15, v100, v101
	v_max3_f32 v15, v15, v102, v103
	v_max3_f32 v15, v15, v104, v105
	v_max3_f32 v15, v15, v106, v107
	v_max3_f32 v15, v15, v108, v109
	v_max3_f32 v15, v15, v110, v111
	s_waitcnt lgkmcnt(6)
	v_mfma_f32_32x32x16_bf16 v[80:95], v[18:21], v[236:239], v[80:95]
	ds_read_b64_tr_b16 v[236:237], v190 offset:8192
	ds_read_b64_tr_b16 v[238:239], v190 offset:10240
	v_mov_b32_e32 v17, v15
	s_nop 1
	v_permlane32_swap_b32_e32 v15, v17
	v_max_f32_e32 v17, v17, v17
	v_max_f32_e32 v15, v15, v15
	s_waitcnt lgkmcnt(6)
	v_mfma_f32_32x32x16_bf16 v[64:79], v[18:21], v[240:243], v[64:79]
	ds_read_b64_tr_b16 v[240:241], v190 offset:8704
	ds_read_b64_tr_b16 v[242:243], v190 offset:10752
	v_max_f32_e32 v15, v15, v17
	v_sub_f32_e32 v17, v15, v208
	v_mul_f32_e32 v17, 0x3d93cd3a, v17
	v_cmp_ge_f32_e32 vcc, s86, v17
	v_max_f32_e32 v17, v208, v208
	s_waitcnt lgkmcnt(6)
	v_mfma_f32_32x32x16_bf16 v[80:95], v[22:25], v[246:249], v[80:95]
	ds_read_b64_tr_b16 v[246:247], v190 offset:12288
	ds_read_b64_tr_b16 v[248:249], v190 offset:14336
	v_max_f32_e32 v17, v17, v15
	v_sub_f32_e32 v15, v208, v17
	v_mul_f32_e32 v15, 0x3dd53b94, v15
	v_exp_f32_e32 v15, v15
	s_cmp_eq_u64 vcc, exec
	s_waitcnt lgkmcnt(6)
	v_mfma_f32_32x32x16_bf16 v[64:79], v[22:25], v[250:253], v[64:79]
	ds_read_b64_tr_b16 v[250:251], v190 offset:12800
	ds_read_b64_tr_b16 v[252:253], v190 offset:14848
	s_cselect_b64 s[10:11], -1, 0
	v_cndmask_b32_e64 v180, v17, v208, s[10:11]
	v_cndmask_b32_e64 v15, v15, 1.0, s[10:11]
	v_mul_f32_e32 v219, 0xbdd53b94, v180
	v_fmamk_f32 v216, v112, 0x3dd53b94, v219
	s_waitcnt lgkmcnt(6)
	v_mfma_f32_32x32x16_bf16 v[80:95], v[26:29], v[236:239], v[80:95]
	ds_read_b64_tr_b16 v[236:237], v190 offset:1024
	ds_read_b64_tr_b16 v[238:239], v190 offset:3072
	v_fmamk_f32 v218, v113, 0x3dd53b94, v219
	v_fmamk_f32 v214, v114, 0x3dd53b94, v219
	v_fmamk_f32 v217, v115, 0x3dd53b94, v219
	v_fmamk_f32 v212, v116, 0x3dd53b94, v219
	v_fmamk_f32 v215, v117, 0x3dd53b94, v219
	s_waitcnt lgkmcnt(6)
	v_mfma_f32_32x32x16_bf16 v[64:79], v[26:29], v[240:243], v[64:79]
	ds_read_b64_tr_b16 v[240:241], v190 offset:1536
	ds_read_b64_tr_b16 v[242:243], v190 offset:3584
	v_fmamk_f32 v211, v118, 0x3dd53b94, v219
	v_fmamk_f32 v213, v119, 0x3dd53b94, v219
	v_fmamk_f32 v182, v120, 0x3dd53b94, v219
	v_fmamk_f32 v208, v121, 0x3dd53b94, v219
	v_fmamk_f32 v183, v123, 0x3dd53b94, v219
	s_waitcnt lgkmcnt(6)
	v_mfma_f32_32x32x16_bf16 v[80:95], v[168:171], v[246:249], v[80:95]
	ds_read_b64_tr_b16 v[246:247], v190 offset:5120
	ds_read_b64_tr_b16 v[248:249], v190 offset:7168
	v_fmamk_f32 v181, v125, 0x3dd53b94, v219
	v_exp_f32_e32 v216, v216
	v_fmamk_f32 v220, v96, 0x3dd53b94, v219
	v_exp_f32_e32 v218, v218
	s_waitcnt lgkmcnt(6)
	v_mfma_f32_32x32x16_bf16 v[64:79], v[168:171], v[250:253], v[64:79]
	ds_read_b64_tr_b16 v[250:251], v190 offset:5632
	ds_read_b64_tr_b16 v[252:253], v190 offset:7680
	v_fmamk_f32 v221, v97, 0x3dd53b94, v219
	v_exp_f32_e32 v214, v214
	v_fmamk_f32 v222, v98, 0x3dd53b94, v219
	v_exp_f32_e32 v217, v217
	s_waitcnt lgkmcnt(6)
	v_mfma_f32_32x32x16_bf16 v[48:63], v[18:21], v[236:239], v[48:63]
	ds_read_b64_tr_b16 v[236:237], v190 offset:9216
	ds_read_b64_tr_b16 v[238:239], v190 offset:11264
	v_fmamk_f32 v223, v99, 0x3dd53b94, v219
	v_exp_f32_e32 v212, v212
	v_fmamk_f32 v224, v100, 0x3dd53b94, v219
	v_exp_f32_e32 v215, v215
	s_waitcnt lgkmcnt(6)
	v_mfma_f32_32x32x16_bf16 v[32:47], v[18:21], v[240:243], v[32:47]
	ds_read_b64_tr_b16 v[240:241], v190 offset:9728
	ds_read_b64_tr_b16 v[242:243], v190 offset:11776
	v_fmamk_f32 v225, v101, 0x3dd53b94, v219
	v_exp_f32_e32 v211, v211
	v_fmamk_f32 v226, v102, 0x3dd53b94, v219
	v_exp_f32_e32 v213, v213
	s_waitcnt lgkmcnt(6)
	v_mfma_f32_32x32x16_bf16 v[48:63], v[22:25], v[246:249], v[48:63]
	ds_read_b64_tr_b16 v[246:247], v190 offset:13312
	ds_read_b64_tr_b16 v[248:249], v190 offset:15360
	v_fmamk_f32 v227, v103, 0x3dd53b94, v219
	v_fmamk_f32 v228, v104, 0x3dd53b94, v219
	v_fmamk_f32 v229, v105, 0x3dd53b94, v219
	v_fmamk_f32 v230, v106, 0x3dd53b94, v219
	s_waitcnt lgkmcnt(6)
	v_mfma_f32_32x32x16_bf16 v[32:47], v[22:25], v[250:253], v[32:47]
	ds_read_b64_tr_b16 v[250:251], v190 offset:13824
	ds_read_b64_tr_b16 v[252:253], v190 offset:15872
	v_fmamk_f32 v231, v107, 0x3dd53b94, v219
	v_fmamk_f32 v232, v108, 0x3dd53b94, v219
	v_fmamk_f32 v233, v109, 0x3dd53b94, v219
	v_fmamk_f32 v234, v110, 0x3dd53b94, v219
	s_branch .Lh1_kw

.Lh1_kw:
	s_waitcnt vmcnt(0)
	ds_write_b128 v202, v[6:9] offset:32768
	ds_write_b128 v202, v[160:163] offset:45056
	ds_write_b128 v203, v[164:167] offset:32768
	s_add_i32 s10, s54, 1
	s_waitcnt lgkmcnt(0)
	s_barrier
	ds_write_b128 v200, v[2:5]
	ds_write_b128 v201, v[10:13]
	s_cmp_gt_i32 s10, s5
	s_cbranch_scc1 .Lh2_skip_g3
	v_mfma_f32_32x32x16_bf16 v[48:63], v[26:29], v[236:239], v[48:63]
	ds_read_b128 v[236:239], v196 offset:32768
	v_mfma_f32_32x32x16_bf16 v[32:47], v[26:29], v[240:243], v[32:47]
	ds_read_b128 v[240:243], v196 offset:45056
	v_mfma_f32_32x32x16_bf16 v[48:63], v[168:171], v[246:249], v[48:63]
	ds_read_b128 v[246:249], v197 offset:32768
	v_mfma_f32_32x32x16_bf16 v[32:47], v[168:171], v[250:253], v[32:47]
	ds_read_b128 v[250:253], v197 offset:45056
	ds_read_b128 v[6:9], v195
	ds_read_b128 v[10:13], v195 offset:1024
	ds_read_b128 v[2:5], v195 offset:2048
	v_cmp_gt_f32_e32 vcc, 1.0, v15
	s_cbranch_vccz .Lqh2_norsc
	s_and_saveexec_b64 s[78:79], s[8:9]
	ds_write_b32 v192, v15 offset:128
	s_or_b64 exec, exec, s[78:79]
	s_waitcnt lgkmcnt(0)
	ds_read_b128 v[18:21], v189 offset:224
	ds_read_b128 v[22:25], v189 offset:192
	ds_read_b128 v[26:29], v189 offset:160
	ds_read_b128 v[168:171], v189 offset:128
	s_waitcnt lgkmcnt(3)
	v_pk_mul_f32 v[94:95], v[94:95], v[20:21]
	s_waitcnt lgkmcnt(2)
	v_pk_mul_f32 v[90:91], v[90:91], v[24:25]
	s_waitcnt lgkmcnt(1)
	v_pk_mul_f32 v[86:87], v[86:87], v[28:29]
	s_waitcnt lgkmcnt(0)
	v_pk_mul_f32 v[82:83], v[82:83], v[170:171]
	v_pk_mul_f32 v[92:93], v[92:93], v[18:19]
	v_pk_mul_f32 v[88:89], v[88:89], v[22:23]
	v_pk_mul_f32 v[84:85], v[84:85], v[26:27]
	v_pk_mul_f32 v[80:81], v[80:81], v[168:169]
	v_pk_mul_f32 v[78:79], v[78:79], v[20:21]
	v_pk_mul_f32 v[74:75], v[74:75], v[24:25]
	v_pk_mul_f32 v[70:71], v[70:71], v[28:29]
	v_pk_mul_f32 v[66:67], v[66:67], v[170:171]
	v_pk_mul_f32 v[76:77], v[76:77], v[18:19]
	v_pk_mul_f32 v[72:73], v[72:73], v[22:23]
	v_pk_mul_f32 v[68:69], v[68:69], v[26:27]
	v_pk_mul_f32 v[64:65], v[64:65], v[168:169]
	v_pk_mul_f32 v[62:63], v[62:63], v[20:21]
	v_pk_mul_f32 v[58:59], v[58:59], v[24:25]
	v_pk_mul_f32 v[54:55], v[54:55], v[28:29]
	v_pk_mul_f32 v[50:51], v[50:51], v[170:171]
	v_pk_mul_f32 v[60:61], v[60:61], v[18:19]
	v_pk_mul_f32 v[56:57], v[56:57], v[22:23]
	v_pk_mul_f32 v[52:53], v[52:53], v[26:27]
	v_pk_mul_f32 v[48:49], v[48:49], v[168:169]
	v_pk_mul_f32 v[46:47], v[46:47], v[20:21]
	v_pk_mul_f32 v[42:43], v[42:43], v[24:25]
	v_pk_mul_f32 v[38:39], v[38:39], v[28:29]
	v_pk_mul_f32 v[34:35], v[34:35], v[170:171]
	v_pk_mul_f32 v[44:45], v[44:45], v[18:19]
	v_pk_mul_f32 v[40:41], v[40:41], v[22:23]
	v_pk_mul_f32 v[36:37], v[36:37], v[26:27]
	v_pk_mul_f32 v[32:33], v[32:33], v[168:169]

.Lh2_nomask:
	s_mov_b32 s98, 0
	s_andn2_b64 vcc, exec, s[76:77]
	s_cbranch_vccnz .Lh2_nopv
	s_mov_b32 s98, 1
	ds_read_b64_tr_b16 v[236:237], v190 offset:16384
	ds_read_b64_tr_b16 v[238:239], v190 offset:18432
	ds_read_b64_tr_b16 v[240:241], v190 offset:16896
	ds_read_b64_tr_b16 v[242:243], v190 offset:18944
	ds_read_b64_tr_b16 v[246:247], v190 offset:20480
	ds_read_b64_tr_b16 v[248:249], v190 offset:22528
	ds_read_b64_tr_b16 v[250:251], v190 offset:20992
	ds_read_b64_tr_b16 v[252:253], v190 offset:23040
	v_max_f32_e32 v255, v113, v113
	v_max_f32_e32 v245, v112, v112
	v_max_f32_e32 v255, v245, v255
	v_max3_f32 v255, v255, v114, v115
	v_max3_f32 v255, v255, v116, v117
	v_max3_f32 v255, v255, v118, v119
	v_max3_f32 v255, v255, v120, v121
	v_max3_f32 v255, v255, v122, v123
	v_max3_f32 v255, v255, v124, v125
	v_max3_f32 v255, v255, v126, v127
	v_max3_f32 v255, v255, v96, v97
	v_max3_f32 v255, v255, v98, v99
	v_max3_f32 v255, v255, v100, v101
	v_max3_f32 v255, v255, v102, v103
	v_max3_f32 v255, v255, v104, v105
	v_max3_f32 v255, v255, v106, v107
	v_max3_f32 v255, v255, v108, v109
	v_max3_f32 v255, v255, v110, v111
	s_waitcnt lgkmcnt(6)
	v_mfma_f32_32x32x16_bf16 v[80:95], v[18:21], v[236:239], v[80:95]
	ds_read_b64_tr_b16 v[236:237], v190 offset:24576
	ds_read_b64_tr_b16 v[238:239], v190 offset:26624
	v_mov_b32_e32 v245, v255
	s_nop 1
	v_permlane32_swap_b32_e32 v255, v245
	v_max_f32_e32 v245, v245, v245
	v_max_f32_e32 v255, v255, v255
	s_waitcnt lgkmcnt(6)
	v_mfma_f32_32x32x16_bf16 v[64:79], v[18:21], v[240:243], v[64:79]
	ds_read_b64_tr_b16 v[240:241], v190 offset:25088
	ds_read_b64_tr_b16 v[242:243], v190 offset:27136
	v_max_f32_e32 v255, v255, v245
	v_sub_f32_e32 v245, v255, v180
	v_mul_f32_e32 v245, 0x3d93cd3a, v245
	v_cmp_ge_f32_e32 vcc, s86, v245
	s_cmp_eq_u64 vcc, exec
	s_waitcnt lgkmcnt(6)
	v_mfma_f32_32x32x16_bf16 v[80:95], v[22:25], v[246:249], v[80:95]
	ds_read_b64_tr_b16 v[246:247], v190 offset:28672
	ds_read_b64_tr_b16 v[248:249], v190 offset:30720
	s_cselect_b64 s[10:11], -1, 0
	v_max_f32_e32 v235, v180, v180
	v_max_f32_e32 v245, v235, v255
	v_sub_f32_e32 v235, v180, v245
	v_mul_f32_e32 v235, 0x3dd53b94, v235
	s_waitcnt lgkmcnt(6)
	v_mfma_f32_32x32x16_bf16 v[64:79], v[22:25], v[250:253], v[64:79]
	ds_read_b64_tr_b16 v[250:251], v190 offset:29184
	ds_read_b64_tr_b16 v[252:253], v190 offset:31232
	v_exp_f32_e32 v235, v235
	v_cndmask_b32_e64 v208, v245, v180, s[10:11]
	v_cndmask_b32_e64 v235, v235, 1.0, s[10:11]
	v_mul_f32_e32 v254, 0xbdd53b94, v208
	v_mov_b32_e32 v213, v254
	s_waitcnt lgkmcnt(6)
	v_mfma_f32_32x32x16_bf16 v[80:95], v[26:29], v[236:239], v[80:95]
	ds_read_b64_tr_b16 v[236:237], v190 offset:17408
	ds_read_b64_tr_b16 v[238:239], v190 offset:19456
	v_fmamk_f32 v224, v112, 0x3dd53b94, v254
	v_fmamk_f32 v226, v113, 0x3dd53b94, v254
	v_fmamk_f32 v222, v114, 0x3dd53b94, v254
	v_fmamk_f32 v225, v115, 0x3dd53b94, v254
	v_fmamk_f32 v220, v116, 0x3dd53b94, v254
	s_waitcnt lgkmcnt(6)
	v_mfma_f32_32x32x16_bf16 v[64:79], v[26:29], v[240:243], v[64:79]
	ds_read_b64_tr_b16 v[240:241], v190 offset:17920
	ds_read_b64_tr_b16 v[242:243], v190 offset:19968
	v_fmamk_f32 v223, v117, 0x3dd53b94, v254
	v_fmamk_f32 v219, v118, 0x3dd53b94, v254
	v_fmamk_f32 v221, v119, 0x3dd53b94, v254
	v_fmamk_f32 v216, v120, 0x3dd53b94, v254
	v_fmamk_f32 v218, v121, 0x3dd53b94, v254
	s_waitcnt lgkmcnt(6)
	v_mfma_f32_32x32x16_bf16 v[80:95], v[168:171], v[246:249], v[80:95]
	ds_read_b64_tr_b16 v[246:247], v190 offset:21504
	ds_read_b64_tr_b16 v[248:249], v190 offset:23552
	v_fmamk_f32 v214, v122, 0x3dd53b94, v254
	v_fmamk_f32 v217, v123, 0x3dd53b94, v254
	v_fmamk_f32 v212, v124, 0x3dd53b94, v254
	v_fmamk_f32 v215, v125, 0x3dd53b94, v254
	v_fmamk_f32 v211, v126, 0x3dd53b94, v254
	s_waitcnt lgkmcnt(6)
	v_mfma_f32_32x32x16_bf16 v[64:79], v[168:171], v[250:253], v[64:79]
	ds_read_b64_tr_b16 v[250:251], v190 offset:22016
	ds_read_b64_tr_b16 v[252:253], v190 offset:24064
	v_fmac_f32_e32 v213, 0x3dd53b94, v127
	v_exp_f32_e32 v224, v224
	v_exp_f32_e32 v226, v226
	v_exp_f32_e32 v222, v222
	v_exp_f32_e32 v225, v225
	s_waitcnt lgkmcnt(6)
	v_mfma_f32_32x32x16_bf16 v[48:63], v[18:21], v[236:239], v[48:63]
	ds_read_b64_tr_b16 v[236:237], v190 offset:25600
	ds_read_b64_tr_b16 v[238:239], v190 offset:27648
	v_exp_f32_e32 v220, v220
	v_exp_f32_e32 v223, v223
	v_exp_f32_e32 v219, v219
	v_exp_f32_e32 v221, v221
	s_waitcnt lgkmcnt(6)
	v_mfma_f32_32x32x16_bf16 v[32:47], v[18:21], v[240:243], v[32:47]
	ds_read_b64_tr_b16 v[240:241], v190 offset:26112
	ds_read_b64_tr_b16 v[242:243], v190 offset:28160
	v_exp_f32_e32 v216, v216
	v_exp_f32_e32 v218, v218
	v_exp_f32_e32 v214, v214
	v_exp_f32_e32 v217, v217
	s_waitcnt lgkmcnt(6)
	v_mfma_f32_32x32x16_bf16 v[48:63], v[22:25], v[246:249], v[48:63]
	ds_read_b64_tr_b16 v[246:247], v190 offset:29696
	ds_read_b64_tr_b16 v[248:249], v190 offset:31744
	v_exp_f32_e32 v212, v212
	v_exp_f32_e32 v215, v215
	v_exp_f32_e32 v211, v211
	v_exp_f32_e32 v213, v213
	s_waitcnt lgkmcnt(6)
	v_mfma_f32_32x32x16_bf16 v[32:47], v[22:25], v[250:253], v[32:47]
	ds_read_b64_tr_b16 v[250:251], v190 offset:30208
	ds_read_b64_tr_b16 v[252:253], v190 offset:32256
	v_fmamk_f32 v182, v96, 0x3dd53b94, v254
	v_fmamk_f32 v183, v97, 0x3dd53b94, v254
	v_fmamk_f32 v180, v98, 0x3dd53b94, v254
	v_fmamk_f32 v181, v99, 0x3dd53b94, v254
	s_branch .Lh2_kw
